# v50 + non-temporal hint (nt) on the FFN-up activation write-through stores (output is consumed two phases later from another XCD, keeping it out of L2 helps the K-loop tiles)
# speedup vs baseline: 1.0150x; 1.0087x over previous
.LBB0_723:
	v_lshl_add_u32 v184, s6, 8, v186
	v_lshlrev_b32_e32 v146, 6, v184
	v_mov_b32_e32 v147, 0
	v_lshl_add_u64 v[146:147], v[140:141], 0, v[146:147]
	s_mov_b64 s[100:101], 0x2000
	v_lshl_add_u64 v[148:149], v[146:147], 0, s[100:101]
	global_load_dwordx4 v[206:209], v[146:147], off
	global_load_dwordx4 v[210:213], v[146:147], off offset:1024
	global_load_dwordx4 v[214:217], v[146:147], off offset:2048
	global_load_dwordx4 v[218:221], v[146:147], off offset:3072
	global_load_dwordx4 v[222:225], v[148:149], off
	global_load_dwordx4 v[226:229], v[148:149], off offset:1024
	global_load_dwordx4 v[230:233], v[148:149], off offset:2048
	global_load_dwordx4 v[234:237], v[148:149], off offset:3072
	v_lshl_or_b32 v150, s46, 7, v188
	v_mov_b32_e32 v151, 0
	v_lshlrev_b32_e32 v147, 2, v150
	v_mov_b32_e32 v146, v147
	v_mov_b32_e32 v147, 0
	v_lshl_add_u64 v[148:149], s[30:31], 0, v[146:147]
	global_load_dwordx4 v[168:171], v[148:149], off
	global_load_dwordx4 v[192:195], v[148:149], off offset:16
	v_lshl_add_u64 v[148:149], s[0:1], 0, v[146:147]
	global_load_dwordx4 v[172:175], v[148:149], off
	global_load_dwordx4 v[196:199], v[148:149], off offset:16
	v_lshl_add_u64 v[148:149], s[48:49], 0, v[146:147]
	global_load_dwordx4 v[176:179], v[148:149], off
	global_load_dwordx4 v[200:203], v[148:149], off offset:16
	v_lshl_add_u64 v[148:149], s[82:83], 0, v[146:147]
	global_load_dwordx4 v[180:183], v[148:149], off
	global_load_dwordx4 v[238:241], v[148:149], off offset:16
	v_mul_lo_u32 v185, v184, s67
	v_add_lshl_u32 v185, v185, v150, 1
	s_lshl_b32 s5, s6, 2
	s_add_i32 s5, s5, s80
	s_mul_hi_i32 s7, s5, 0x8400
	s_mul_i32 s5, s5, 0x8400
	s_add_u32 s6, s56, s5
	s_addc_u32 s7, s57, s7
	v_lshl_add_u64 v[246:247], v[150:151], 1, s[6:7]
	v_lshl_add_u64 v[246:247], v[246:247], 0, v[138:139]
	v_xor_b32_e32 v148, 16, v191
	v_xor_b32_e32 v149, 32, v191
	v_lshlrev_b32_e32 v148, 2, v148
	v_lshlrev_b32_e32 v149, 2, v149
	s_mov_b32 s100, 0xbfb8aa3b
	s_waitcnt vmcnt(0)
	v_add_f32_e32 v206, v206, v207
	v_add_f32_e32 v208, v208, v209
	v_add_f32_e32 v210, v210, v211
	v_add_f32_e32 v212, v212, v213
	v_add_f32_e32 v214, v214, v215
	v_add_f32_e32 v216, v216, v217
	v_add_f32_e32 v218, v218, v219
	v_add_f32_e32 v220, v220, v221
	v_add_f32_e32 v222, v222, v223
	v_add_f32_e32 v224, v224, v225
	v_add_f32_e32 v226, v226, v227
	v_add_f32_e32 v228, v228, v229
	v_add_f32_e32 v230, v230, v231
	v_add_f32_e32 v232, v232, v233
	v_add_f32_e32 v234, v234, v235
	v_add_f32_e32 v236, v236, v237
	v_add_f32_e32 v206, v206, v208
	v_add_f32_e32 v210, v210, v212
	v_add_f32_e32 v214, v214, v216
	v_add_f32_e32 v218, v218, v220
	v_add_f32_e32 v222, v222, v224
	v_add_f32_e32 v226, v226, v228
	v_add_f32_e32 v230, v230, v232
	v_add_f32_e32 v234, v234, v236
	ds_bpermute_b32 v207, v148, v206
	ds_bpermute_b32 v211, v148, v210
	ds_bpermute_b32 v215, v148, v214
	ds_bpermute_b32 v219, v148, v218
	ds_bpermute_b32 v223, v148, v222
	ds_bpermute_b32 v227, v148, v226
	ds_bpermute_b32 v231, v148, v230
	ds_bpermute_b32 v235, v148, v234
	s_waitcnt lgkmcnt(0)
	v_add_f32_e32 v206, v206, v207
	v_add_f32_e32 v210, v210, v211
	v_add_f32_e32 v214, v214, v215
	v_add_f32_e32 v218, v218, v219
	v_add_f32_e32 v222, v222, v223
	v_add_f32_e32 v226, v226, v227
	v_add_f32_e32 v230, v230, v231
	v_add_f32_e32 v234, v234, v235
	ds_bpermute_b32 v207, v149, v206
	ds_bpermute_b32 v211, v149, v210
	ds_bpermute_b32 v215, v149, v214
	ds_bpermute_b32 v219, v149, v218
	ds_bpermute_b32 v223, v149, v222
	ds_bpermute_b32 v227, v149, v226
	ds_bpermute_b32 v231, v149, v230
	ds_bpermute_b32 v235, v149, v234
	s_waitcnt lgkmcnt(0)
	v_add_f32_e32 v206, v206, v207
	v_add_f32_e32 v210, v210, v211
	v_add_f32_e32 v214, v214, v215
	v_add_f32_e32 v218, v218, v219
	v_add_f32_e32 v222, v222, v223
	v_add_f32_e32 v226, v226, v227
	v_add_f32_e32 v230, v230, v231
	v_add_f32_e32 v234, v234, v235
	v_pk_mul_f32 v[168:169], v[168:169], s[100:101] op_sel_hi:[1,0]
	v_pk_mul_f32 v[170:171], v[170:171], s[100:101] op_sel_hi:[1,0]
	v_pk_mul_f32 v[172:173], v[172:173], s[100:101] op_sel_hi:[1,0]
	v_pk_mul_f32 v[174:175], v[174:175], s[100:101] op_sel_hi:[1,0]
	v_pk_mul_f32 v[176:177], v[176:177], s[100:101] op_sel_hi:[1,0]
	v_pk_mul_f32 v[178:179], v[178:179], s[100:101] op_sel_hi:[1,0]
	v_pk_mul_f32 v[180:181], v[180:181], s[100:101] op_sel_hi:[1,0]
	v_pk_mul_f32 v[182:183], v[182:183], s[100:101] op_sel_hi:[1,0]
	v_pk_mul_f32 v[192:193], v[192:193], s[100:101] op_sel_hi:[1,0]
	v_pk_mul_f32 v[194:195], v[194:195], s[100:101] op_sel_hi:[1,0]
	v_pk_mul_f32 v[196:197], v[196:197], s[100:101] op_sel_hi:[1,0]
	v_pk_mul_f32 v[198:199], v[198:199], s[100:101] op_sel_hi:[1,0]
	v_pk_mul_f32 v[200:201], v[200:201], s[100:101] op_sel_hi:[1,0]
	v_pk_mul_f32 v[202:203], v[202:203], s[100:101] op_sel_hi:[1,0]
	v_pk_mul_f32 v[238:239], v[238:239], s[100:101] op_sel_hi:[1,0]
	v_pk_mul_f32 v[240:241], v[240:241], s[100:101] op_sel_hi:[1,0]
	v_fmamk_f32 v206, v206, 0x3a800000, v154
	v_cmp_gt_f32_e32 vcc, s84, v206
	v_mul_f32_e32 v207, 0x4b800000, v206
	s_nop 0
	v_cndmask_b32_e32 v206, v206, v207, vcc
	v_rsq_f32_e32 v206, v206
	s_nop 0
	v_mul_f32_e32 v207, 0x45800000, v206
	v_cndmask_b32_e32 v206, v206, v207, vcc
	v_mul_f32_e32 v208, 0xbf317218, v206
	v_fmamk_f32 v210, v210, 0x3a800000, v154
	v_cmp_gt_f32_e32 vcc, s84, v210
	v_mul_f32_e32 v211, 0x4b800000, v210
	s_nop 0
	v_cndmask_b32_e32 v210, v210, v211, vcc
	v_rsq_f32_e32 v210, v210
	s_nop 0
	v_mul_f32_e32 v211, 0x45800000, v210
	v_cndmask_b32_e32 v210, v210, v211, vcc
	v_mul_f32_e32 v212, 0xbf317218, v210
	v_fmamk_f32 v214, v214, 0x3a800000, v154
	v_cmp_gt_f32_e32 vcc, s84, v214
	v_mul_f32_e32 v215, 0x4b800000, v214
	s_nop 0
	v_cndmask_b32_e32 v214, v214, v215, vcc
	v_rsq_f32_e32 v214, v214
	s_nop 0
	v_mul_f32_e32 v215, 0x45800000, v214
	v_cndmask_b32_e32 v214, v214, v215, vcc
	v_mul_f32_e32 v216, 0xbf317218, v214
	v_fmamk_f32 v218, v218, 0x3a800000, v154
	v_cmp_gt_f32_e32 vcc, s84, v218
	v_mul_f32_e32 v219, 0x4b800000, v218
	s_nop 0
	v_cndmask_b32_e32 v218, v218, v219, vcc
	v_rsq_f32_e32 v218, v218
	s_nop 0
	v_mul_f32_e32 v219, 0x45800000, v218
	v_cndmask_b32_e32 v218, v218, v219, vcc
	v_mul_f32_e32 v220, 0xbf317218, v218
	v_fmamk_f32 v222, v222, 0x3a800000, v154
	v_cmp_gt_f32_e32 vcc, s84, v222
	v_mul_f32_e32 v223, 0x4b800000, v222
	s_nop 0
	v_cndmask_b32_e32 v222, v222, v223, vcc
	v_rsq_f32_e32 v222, v222
	s_nop 0
	v_mul_f32_e32 v223, 0x45800000, v222
	v_cndmask_b32_e32 v222, v222, v223, vcc
	v_mul_f32_e32 v224, 0xbf317218, v222
	v_fmamk_f32 v226, v226, 0x3a800000, v154
	v_cmp_gt_f32_e32 vcc, s84, v226
	v_mul_f32_e32 v227, 0x4b800000, v226
	s_nop 0
	v_cndmask_b32_e32 v226, v226, v227, vcc
	v_rsq_f32_e32 v226, v226
	s_nop 0
	v_mul_f32_e32 v227, 0x45800000, v226
	v_cndmask_b32_e32 v226, v226, v227, vcc
	v_mul_f32_e32 v228, 0xbf317218, v226
	v_fmamk_f32 v230, v230, 0x3a800000, v154
	v_cmp_gt_f32_e32 vcc, s84, v230
	v_mul_f32_e32 v231, 0x4b800000, v230
	s_nop 0
	v_cndmask_b32_e32 v230, v230, v231, vcc
	v_rsq_f32_e32 v230, v230
	s_nop 0
	v_mul_f32_e32 v231, 0x45800000, v230
	v_cndmask_b32_e32 v230, v230, v231, vcc
	v_mul_f32_e32 v232, 0xbf317218, v230
	v_fmamk_f32 v234, v234, 0x3a800000, v154
	v_cmp_gt_f32_e32 vcc, s84, v234
	v_mul_f32_e32 v235, 0x4b800000, v234
	s_nop 0
	v_cndmask_b32_e32 v234, v234, v235, vcc
	v_rsq_f32_e32 v234, v234
	s_nop 0
	v_mul_f32_e32 v235, 0x45800000, v234
	v_cndmask_b32_e32 v234, v234, v235, vcc
	v_mul_f32_e32 v236, 0xbf317218, v234
	s_and_saveexec_b64 s[6:7], s[40:41]
	v_pk_mul_f32 v[242:243], v[124:125], v[206:207] op_sel_hi:[1,0]
	v_pk_mul_f32 v[244:245], v[126:127], v[206:207] op_sel_hi:[1,0]
	s_mov_b32 s100, 0x5800
	s_mov_b32 s101, 0
	v_cvt_pk_bf16_f32 v242, v242, v243
	v_cvt_pk_bf16_f32 v243, v244, v245
	v_lshl_add_u64 v[150:151], v[246:247], 0, s[100:101]
	global_store_dwordx2 v[150:151], v[242:243], off
	s_or_b64 exec, exec, s[6:7]
	v_pk_mul_f32 v[128:129], v[128:129], v[206:207] op_sel_hi:[1,0]
	v_pk_mul_f32 v[130:131], v[130:131], v[206:207] op_sel_hi:[1,0]
	v_pk_mul_f32 v[124:125], v[124:125], v[208:209] op_sel_hi:[1,0]
	v_pk_mul_f32 v[126:127], v[126:127], v[208:209] op_sel_hi:[1,0]
	v_pk_fma_f32 v[146:147], v[176:177], v[128:129], v[180:181]
	v_pk_fma_f32 v[148:149], v[178:179], v[130:131], v[182:183]
	v_fmac_f32_dpp v146, v128, v172 row_shr:1 row_mask:0xf bank_mask:0xf bound_ctrl:1
	v_fmac_f32_dpp v147, v129, v173 row_shr:1 row_mask:0xf bank_mask:0xf bound_ctrl:1
	v_fmac_f32_dpp v148, v130, v174 row_shr:1 row_mask:0xf bank_mask:0xf bound_ctrl:1
	v_fmac_f32_dpp v149, v131, v175 row_shr:1 row_mask:0xf bank_mask:0xf bound_ctrl:1
	v_fmac_f32_dpp v146, v128, v168 row_shr:2 row_mask:0xf bank_mask:0xf bound_ctrl:1
	v_fmac_f32_dpp v147, v129, v169 row_shr:2 row_mask:0xf bank_mask:0xf bound_ctrl:1
	v_fmac_f32_dpp v148, v130, v170 row_shr:2 row_mask:0xf bank_mask:0xf bound_ctrl:1
	v_fmac_f32_dpp v149, v131, v171 row_shr:2 row_mask:0xf bank_mask:0xf bound_ctrl:1
	v_exp_f32_e32 v242, v146
	v_exp_f32_e32 v243, v147
	v_exp_f32_e32 v244, v148
	v_exp_f32_e32 v245, v149
	v_pk_mul_f32 v[146:147], v[146:147], v[124:125]
	v_pk_mul_f32 v[148:149], v[148:149], v[126:127]
	v_pk_add_f32 v[242:243], v[242:243], 1.0 op_sel_hi:[1,0]
	v_pk_add_f32 v[244:245], v[244:245], 1.0 op_sel_hi:[1,0]
	v_rcp_f32_e32 v242, v242
	v_rcp_f32_e32 v243, v243
	v_rcp_f32_e32 v244, v244
	v_rcp_f32_e32 v245, v245
	v_cvt_pk_bf16_f32 v126, v128, v129
	v_cvt_pk_bf16_f32 v127, v130, v131
	v_pk_mul_f32 v[146:147], v[146:147], v[242:243]
	v_pk_mul_f32 v[148:149], v[148:149], v[244:245]
	s_mov_b32 s100, 0x2c00
	s_mov_b32 s101, 0
	s_and_saveexec_b64 s[6:7], s[40:41]
	v_lshl_add_u64 v[150:151], v[246:247], 0, s[100:101]
	global_store_dwordx2 v[150:151], v[126:127], off
	s_or_b64 exec, exec, s[6:7]
	v_cvt_pk_bf16_f32 v124, v146, v147
	v_cvt_pk_bf16_f32 v125, v148, v149
	v_pk_mul_f32 v[120:121], v[120:121], v[210:211] op_sel_hi:[1,0]
	v_pk_mul_f32 v[122:123], v[122:123], v[210:211] op_sel_hi:[1,0]
	v_pk_mul_f32 v[116:117], v[116:117], v[212:213] op_sel_hi:[1,0]
	v_pk_mul_f32 v[118:119], v[118:119], v[212:213] op_sel_hi:[1,0]
	v_pk_fma_f32 v[146:147], v[176:177], v[120:121], v[180:181]
	v_pk_fma_f32 v[148:149], v[178:179], v[122:123], v[182:183]
	v_fmac_f32_dpp v146, v120, v172 row_shr:1 row_mask:0xf bank_mask:0xf bound_ctrl:1
	v_fmac_f32_dpp v147, v121, v173 row_shr:1 row_mask:0xf bank_mask:0xf bound_ctrl:1
	v_fmac_f32_dpp v148, v122, v174 row_shr:1 row_mask:0xf bank_mask:0xf bound_ctrl:1
	v_fmac_f32_dpp v149, v123, v175 row_shr:1 row_mask:0xf bank_mask:0xf bound_ctrl:1
	v_fmac_f32_dpp v146, v128, v172 row_shl:15 row_mask:0xf bank_mask:0xf
	v_fmac_f32_dpp v147, v129, v173 row_shl:15 row_mask:0xf bank_mask:0xf
	v_fmac_f32_dpp v148, v130, v174 row_shl:15 row_mask:0xf bank_mask:0xf
	v_fmac_f32_dpp v149, v131, v175 row_shl:15 row_mask:0xf bank_mask:0xf
	v_fmac_f32_dpp v146, v120, v168 row_shr:2 row_mask:0xf bank_mask:0xf bound_ctrl:1
	v_fmac_f32_dpp v147, v121, v169 row_shr:2 row_mask:0xf bank_mask:0xf bound_ctrl:1
	v_fmac_f32_dpp v148, v122, v170 row_shr:2 row_mask:0xf bank_mask:0xf bound_ctrl:1
	v_fmac_f32_dpp v149, v123, v171 row_shr:2 row_mask:0xf bank_mask:0xf bound_ctrl:1
	v_fmac_f32_dpp v146, v128, v168 row_shl:14 row_mask:0xf bank_mask:0xf
	v_fmac_f32_dpp v147, v129, v169 row_shl:14 row_mask:0xf bank_mask:0xf
	v_fmac_f32_dpp v148, v130, v170 row_shl:14 row_mask:0xf bank_mask:0xf
	v_fmac_f32_dpp v149, v131, v171 row_shl:14 row_mask:0xf bank_mask:0xf
	v_exp_f32_e32 v242, v146
	v_exp_f32_e32 v243, v147
	v_exp_f32_e32 v244, v148
	v_exp_f32_e32 v245, v149
	v_pk_mul_f32 v[146:147], v[146:147], v[116:117]
	v_pk_mul_f32 v[148:149], v[148:149], v[118:119]
	v_pk_add_f32 v[242:243], v[242:243], 1.0 op_sel_hi:[1,0]
	v_pk_add_f32 v[244:245], v[244:245], 1.0 op_sel_hi:[1,0]
	v_rcp_f32_e32 v242, v242
	v_rcp_f32_e32 v243, v243
	v_rcp_f32_e32 v244, v244
	v_rcp_f32_e32 v245, v245
	s_nop 0
	v_pk_mul_f32 v[146:147], v[146:147], v[242:243]
	v_pk_mul_f32 v[148:149], v[148:149], v[244:245]
	v_cvt_pk_bf16_f32 v116, v146, v147
	v_cvt_pk_bf16_f32 v117, v148, v149
	v_pk_mul_f32 v[112:113], v[112:113], v[214:215] op_sel_hi:[1,0]
	v_pk_mul_f32 v[114:115], v[114:115], v[214:215] op_sel_hi:[1,0]
	v_pk_mul_f32 v[98:99], v[98:99], v[216:217] op_sel_hi:[1,0]
	v_pk_mul_f32 v[100:101], v[100:101], v[216:217] op_sel_hi:[1,0]
	v_pk_fma_f32 v[146:147], v[176:177], v[112:113], v[180:181]
	v_pk_fma_f32 v[148:149], v[178:179], v[114:115], v[182:183]
	v_fmac_f32_dpp v146, v112, v172 row_shr:1 row_mask:0xf bank_mask:0xf bound_ctrl:1
	v_fmac_f32_dpp v147, v113, v173 row_shr:1 row_mask:0xf bank_mask:0xf bound_ctrl:1
	v_fmac_f32_dpp v148, v114, v174 row_shr:1 row_mask:0xf bank_mask:0xf bound_ctrl:1
	v_fmac_f32_dpp v149, v115, v175 row_shr:1 row_mask:0xf bank_mask:0xf bound_ctrl:1
	v_fmac_f32_dpp v146, v120, v172 row_shl:15 row_mask:0xf bank_mask:0xf
	v_fmac_f32_dpp v147, v121, v173 row_shl:15 row_mask:0xf bank_mask:0xf
	v_fmac_f32_dpp v148, v122, v174 row_shl:15 row_mask:0xf bank_mask:0xf
	v_fmac_f32_dpp v149, v123, v175 row_shl:15 row_mask:0xf bank_mask:0xf
	v_fmac_f32_dpp v146, v112, v168 row_shr:2 row_mask:0xf bank_mask:0xf bound_ctrl:1
	v_fmac_f32_dpp v147, v113, v169 row_shr:2 row_mask:0xf bank_mask:0xf bound_ctrl:1
	v_fmac_f32_dpp v148, v114, v170 row_shr:2 row_mask:0xf bank_mask:0xf bound_ctrl:1
	v_fmac_f32_dpp v149, v115, v171 row_shr:2 row_mask:0xf bank_mask:0xf bound_ctrl:1
	v_fmac_f32_dpp v146, v120, v168 row_shl:14 row_mask:0xf bank_mask:0xf
	v_fmac_f32_dpp v147, v121, v169 row_shl:14 row_mask:0xf bank_mask:0xf
	v_fmac_f32_dpp v148, v122, v170 row_shl:14 row_mask:0xf bank_mask:0xf
	v_fmac_f32_dpp v149, v123, v171 row_shl:14 row_mask:0xf bank_mask:0xf
	v_exp_f32_e32 v242, v146
	v_exp_f32_e32 v243, v147
	v_exp_f32_e32 v244, v148
	v_exp_f32_e32 v245, v149
	v_pk_mul_f32 v[146:147], v[146:147], v[98:99]
	v_pk_mul_f32 v[148:149], v[148:149], v[100:101]
	v_pk_add_f32 v[242:243], v[242:243], 1.0 op_sel_hi:[1,0]
	v_pk_add_f32 v[244:245], v[244:245], 1.0 op_sel_hi:[1,0]
	v_rcp_f32_e32 v242, v242
	v_rcp_f32_e32 v243, v243
	v_rcp_f32_e32 v244, v244
	v_rcp_f32_e32 v245, v245
	s_nop 0
	v_pk_mul_f32 v[146:147], v[146:147], v[242:243]
	v_pk_mul_f32 v[148:149], v[148:149], v[244:245]
	v_cvt_pk_bf16_f32 v98, v146, v147
	v_cvt_pk_bf16_f32 v99, v148, v149
	v_pk_mul_f32 v[108:109], v[108:109], v[218:219] op_sel_hi:[1,0]
	v_pk_mul_f32 v[110:111], v[110:111], v[218:219] op_sel_hi:[1,0]
	v_pk_mul_f32 v[104:105], v[104:105], v[220:221] op_sel_hi:[1,0]
	v_pk_mul_f32 v[106:107], v[106:107], v[220:221] op_sel_hi:[1,0]
	v_pk_fma_f32 v[146:147], v[176:177], v[108:109], v[180:181]
	v_pk_fma_f32 v[148:149], v[178:179], v[110:111], v[182:183]
	v_fmac_f32_dpp v146, v108, v172 row_shr:1 row_mask:0xf bank_mask:0xf bound_ctrl:1
	v_fmac_f32_dpp v147, v109, v173 row_shr:1 row_mask:0xf bank_mask:0xf bound_ctrl:1
	v_fmac_f32_dpp v148, v110, v174 row_shr:1 row_mask:0xf bank_mask:0xf bound_ctrl:1
	v_fmac_f32_dpp v149, v111, v175 row_shr:1 row_mask:0xf bank_mask:0xf bound_ctrl:1
	v_fmac_f32_dpp v146, v112, v172 row_shl:15 row_mask:0xf bank_mask:0xf
	v_fmac_f32_dpp v147, v113, v173 row_shl:15 row_mask:0xf bank_mask:0xf
	v_fmac_f32_dpp v148, v114, v174 row_shl:15 row_mask:0xf bank_mask:0xf
	v_fmac_f32_dpp v149, v115, v175 row_shl:15 row_mask:0xf bank_mask:0xf
	v_fmac_f32_dpp v146, v108, v168 row_shr:2 row_mask:0xf bank_mask:0xf bound_ctrl:1
	v_fmac_f32_dpp v147, v109, v169 row_shr:2 row_mask:0xf bank_mask:0xf bound_ctrl:1
	v_fmac_f32_dpp v148, v110, v170 row_shr:2 row_mask:0xf bank_mask:0xf bound_ctrl:1
	v_fmac_f32_dpp v149, v111, v171 row_shr:2 row_mask:0xf bank_mask:0xf bound_ctrl:1
	v_fmac_f32_dpp v146, v112, v168 row_shl:14 row_mask:0xf bank_mask:0xf
	v_fmac_f32_dpp v147, v113, v169 row_shl:14 row_mask:0xf bank_mask:0xf
	v_fmac_f32_dpp v148, v114, v170 row_shl:14 row_mask:0xf bank_mask:0xf
	v_fmac_f32_dpp v149, v115, v171 row_shl:14 row_mask:0xf bank_mask:0xf
	v_exp_f32_e32 v242, v146
	v_exp_f32_e32 v243, v147
	v_exp_f32_e32 v244, v148
	v_exp_f32_e32 v245, v149
	v_pk_mul_f32 v[146:147], v[146:147], v[104:105]
	v_pk_mul_f32 v[148:149], v[148:149], v[106:107]
	v_pk_add_f32 v[242:243], v[242:243], 1.0 op_sel_hi:[1,0]
	v_pk_add_f32 v[244:245], v[244:245], 1.0 op_sel_hi:[1,0]
	v_rcp_f32_e32 v242, v242
	v_rcp_f32_e32 v243, v243
	v_rcp_f32_e32 v244, v244
	v_rcp_f32_e32 v245, v245
	v_cvt_pk_bf16_f32 v106, v108, v109
	v_cvt_pk_bf16_f32 v107, v110, v111
	v_pk_mul_f32 v[146:147], v[146:147], v[242:243]
	v_pk_mul_f32 v[148:149], v[148:149], v[244:245]
	s_mov_b32 s100, 0xfffecc00
	s_mov_b32 s101, -1
	s_and_saveexec_b64 s[6:7], s[42:43]
	v_lshl_add_u64 v[150:151], v[246:247], 0, s[100:101]
	global_store_dwordx2 v[150:151], v[106:107], off
	s_or_b64 exec, exec, s[6:7]
	v_cvt_pk_bf16_f32 v104, v146, v147
	v_cvt_pk_bf16_f32 v105, v148, v149
	s_and_saveexec_b64 s[6:7], s[40:41]
	v_pk_mul_f32 v[242:243], v[88:89], v[222:223] op_sel_hi:[1,0]
	v_pk_mul_f32 v[244:245], v[90:91], v[222:223] op_sel_hi:[1,0]
	s_mov_b32 s100, 0x16000
	s_mov_b32 s101, 0
	v_cvt_pk_bf16_f32 v242, v242, v243
	v_cvt_pk_bf16_f32 v243, v244, v245
	v_lshl_add_u64 v[150:151], v[246:247], 0, s[100:101]
	global_store_dwordx2 v[150:151], v[242:243], off
	s_or_b64 exec, exec, s[6:7]
	v_pk_mul_f32 v[94:95], v[94:95], v[222:223] op_sel_hi:[1,0]
	v_pk_mul_f32 v[96:97], v[96:97], v[222:223] op_sel_hi:[1,0]
	v_pk_mul_f32 v[88:89], v[88:89], v[224:225] op_sel_hi:[1,0]
	v_pk_mul_f32 v[90:91], v[90:91], v[224:225] op_sel_hi:[1,0]
	v_pk_fma_f32 v[146:147], v[176:177], v[94:95], v[180:181]
	v_pk_fma_f32 v[148:149], v[178:179], v[96:97], v[182:183]
	v_fmac_f32_dpp v146, v94, v172 row_shr:1 row_mask:0xf bank_mask:0xf bound_ctrl:1
	v_fmac_f32_dpp v147, v95, v173 row_shr:1 row_mask:0xf bank_mask:0xf bound_ctrl:1
	v_fmac_f32_dpp v148, v96, v174 row_shr:1 row_mask:0xf bank_mask:0xf bound_ctrl:1
	v_fmac_f32_dpp v149, v97, v175 row_shr:1 row_mask:0xf bank_mask:0xf bound_ctrl:1
	v_fmac_f32_dpp v146, v94, v168 row_shr:2 row_mask:0xf bank_mask:0xf bound_ctrl:1
	v_fmac_f32_dpp v147, v95, v169 row_shr:2 row_mask:0xf bank_mask:0xf bound_ctrl:1
	v_fmac_f32_dpp v148, v96, v170 row_shr:2 row_mask:0xf bank_mask:0xf bound_ctrl:1
	v_fmac_f32_dpp v149, v97, v171 row_shr:2 row_mask:0xf bank_mask:0xf bound_ctrl:1
	v_exp_f32_e32 v242, v146
	v_exp_f32_e32 v243, v147
	v_exp_f32_e32 v244, v148
	v_exp_f32_e32 v245, v149
	v_pk_mul_f32 v[146:147], v[146:147], v[88:89]
	v_pk_mul_f32 v[148:149], v[148:149], v[90:91]
	v_pk_add_f32 v[242:243], v[242:243], 1.0 op_sel_hi:[1,0]
	v_pk_add_f32 v[244:245], v[244:245], 1.0 op_sel_hi:[1,0]
	v_rcp_f32_e32 v242, v242
	v_rcp_f32_e32 v243, v243
	v_rcp_f32_e32 v244, v244
	v_rcp_f32_e32 v245, v245
	v_cvt_pk_bf16_f32 v90, v94, v95
	v_cvt_pk_bf16_f32 v91, v96, v97
	v_pk_mul_f32 v[146:147], v[146:147], v[242:243]
	v_pk_mul_f32 v[148:149], v[148:149], v[244:245]
	s_mov_b32 s100, 0x13400
	s_mov_b32 s101, 0
	s_and_saveexec_b64 s[6:7], s[40:41]
	v_lshl_add_u64 v[150:151], v[246:247], 0, s[100:101]
	global_store_dwordx2 v[150:151], v[90:91], off
	s_or_b64 exec, exec, s[6:7]
	v_cvt_pk_bf16_f32 v88, v146, v147
	v_cvt_pk_bf16_f32 v89, v148, v149
	v_pk_mul_f32 v[84:85], v[84:85], v[226:227] op_sel_hi:[1,0]
	v_pk_mul_f32 v[86:87], v[86:87], v[226:227] op_sel_hi:[1,0]
	v_pk_mul_f32 v[80:81], v[80:81], v[228:229] op_sel_hi:[1,0]
	v_pk_mul_f32 v[82:83], v[82:83], v[228:229] op_sel_hi:[1,0]
	v_pk_fma_f32 v[146:147], v[176:177], v[84:85], v[180:181]
	v_pk_fma_f32 v[148:149], v[178:179], v[86:87], v[182:183]
	v_fmac_f32_dpp v146, v84, v172 row_shr:1 row_mask:0xf bank_mask:0xf bound_ctrl:1
	v_fmac_f32_dpp v147, v85, v173 row_shr:1 row_mask:0xf bank_mask:0xf bound_ctrl:1
	v_fmac_f32_dpp v148, v86, v174 row_shr:1 row_mask:0xf bank_mask:0xf bound_ctrl:1
	v_fmac_f32_dpp v149, v87, v175 row_shr:1 row_mask:0xf bank_mask:0xf bound_ctrl:1
	v_fmac_f32_dpp v146, v94, v172 row_shl:15 row_mask:0xf bank_mask:0xf
	v_fmac_f32_dpp v147, v95, v173 row_shl:15 row_mask:0xf bank_mask:0xf
	v_fmac_f32_dpp v148, v96, v174 row_shl:15 row_mask:0xf bank_mask:0xf
	v_fmac_f32_dpp v149, v97, v175 row_shl:15 row_mask:0xf bank_mask:0xf
	v_fmac_f32_dpp v146, v84, v168 row_shr:2 row_mask:0xf bank_mask:0xf bound_ctrl:1
	v_fmac_f32_dpp v147, v85, v169 row_shr:2 row_mask:0xf bank_mask:0xf bound_ctrl:1
	v_fmac_f32_dpp v148, v86, v170 row_shr:2 row_mask:0xf bank_mask:0xf bound_ctrl:1
	v_fmac_f32_dpp v149, v87, v171 row_shr:2 row_mask:0xf bank_mask:0xf bound_ctrl:1
	v_fmac_f32_dpp v146, v94, v168 row_shl:14 row_mask:0xf bank_mask:0xf
	v_fmac_f32_dpp v147, v95, v169 row_shl:14 row_mask:0xf bank_mask:0xf
	v_fmac_f32_dpp v148, v96, v170 row_shl:14 row_mask:0xf bank_mask:0xf
	v_fmac_f32_dpp v149, v97, v171 row_shl:14 row_mask:0xf bank_mask:0xf
	v_exp_f32_e32 v242, v146
	v_exp_f32_e32 v243, v147
	v_exp_f32_e32 v244, v148
	v_exp_f32_e32 v245, v149
	v_pk_mul_f32 v[146:147], v[146:147], v[80:81]
	v_pk_mul_f32 v[148:149], v[148:149], v[82:83]
	v_pk_add_f32 v[242:243], v[242:243], 1.0 op_sel_hi:[1,0]
	v_pk_add_f32 v[244:245], v[244:245], 1.0 op_sel_hi:[1,0]
	v_rcp_f32_e32 v242, v242
	v_rcp_f32_e32 v243, v243
	v_rcp_f32_e32 v244, v244
	v_rcp_f32_e32 v245, v245
	s_nop 0
	v_pk_mul_f32 v[146:147], v[146:147], v[242:243]
	v_pk_mul_f32 v[148:149], v[148:149], v[244:245]
	v_cvt_pk_bf16_f32 v80, v146, v147
	v_cvt_pk_bf16_f32 v81, v148, v149
	v_pk_mul_f32 v[76:77], v[76:77], v[230:231] op_sel_hi:[1,0]
	v_pk_mul_f32 v[78:79], v[78:79], v[230:231] op_sel_hi:[1,0]
	v_pk_mul_f32 v[72:73], v[72:73], v[232:233] op_sel_hi:[1,0]
	v_pk_mul_f32 v[74:75], v[74:75], v[232:233] op_sel_hi:[1,0]
	v_pk_fma_f32 v[146:147], v[176:177], v[76:77], v[180:181]
	v_pk_fma_f32 v[148:149], v[178:179], v[78:79], v[182:183]
	v_fmac_f32_dpp v146, v76, v172 row_shr:1 row_mask:0xf bank_mask:0xf bound_ctrl:1
	v_fmac_f32_dpp v147, v77, v173 row_shr:1 row_mask:0xf bank_mask:0xf bound_ctrl:1
	v_fmac_f32_dpp v148, v78, v174 row_shr:1 row_mask:0xf bank_mask:0xf bound_ctrl:1
	v_fmac_f32_dpp v149, v79, v175 row_shr:1 row_mask:0xf bank_mask:0xf bound_ctrl:1
	v_fmac_f32_dpp v146, v84, v172 row_shl:15 row_mask:0xf bank_mask:0xf
	v_fmac_f32_dpp v147, v85, v173 row_shl:15 row_mask:0xf bank_mask:0xf
	v_fmac_f32_dpp v148, v86, v174 row_shl:15 row_mask:0xf bank_mask:0xf
	v_fmac_f32_dpp v149, v87, v175 row_shl:15 row_mask:0xf bank_mask:0xf
	v_fmac_f32_dpp v146, v76, v168 row_shr:2 row_mask:0xf bank_mask:0xf bound_ctrl:1
	v_fmac_f32_dpp v147, v77, v169 row_shr:2 row_mask:0xf bank_mask:0xf bound_ctrl:1
	v_fmac_f32_dpp v148, v78, v170 row_shr:2 row_mask:0xf bank_mask:0xf bound_ctrl:1
	v_fmac_f32_dpp v149, v79, v171 row_shr:2 row_mask:0xf bank_mask:0xf bound_ctrl:1
	v_fmac_f32_dpp v146, v84, v168 row_shl:14 row_mask:0xf bank_mask:0xf
	v_fmac_f32_dpp v147, v85, v169 row_shl:14 row_mask:0xf bank_mask:0xf
	v_fmac_f32_dpp v148, v86, v170 row_shl:14 row_mask:0xf bank_mask:0xf
	v_fmac_f32_dpp v149, v87, v171 row_shl:14 row_mask:0xf bank_mask:0xf
	v_exp_f32_e32 v242, v146
	v_exp_f32_e32 v243, v147
	v_exp_f32_e32 v244, v148
	v_exp_f32_e32 v245, v149
	v_pk_mul_f32 v[146:147], v[146:147], v[72:73]
	v_pk_mul_f32 v[148:149], v[148:149], v[74:75]
	v_pk_add_f32 v[242:243], v[242:243], 1.0 op_sel_hi:[1,0]
	v_pk_add_f32 v[244:245], v[244:245], 1.0 op_sel_hi:[1,0]
	v_rcp_f32_e32 v242, v242
	v_rcp_f32_e32 v243, v243
	v_rcp_f32_e32 v244, v244
	v_rcp_f32_e32 v245, v245
	s_nop 0
	v_pk_mul_f32 v[146:147], v[146:147], v[242:243]
	v_pk_mul_f32 v[148:149], v[148:149], v[244:245]
	v_cvt_pk_bf16_f32 v72, v146, v147
	v_cvt_pk_bf16_f32 v73, v148, v149
	v_pk_mul_f32 v[68:69], v[68:69], v[234:235] op_sel_hi:[1,0]
	v_pk_mul_f32 v[70:71], v[70:71], v[234:235] op_sel_hi:[1,0]
	v_pk_mul_f32 v[64:65], v[64:65], v[236:237] op_sel_hi:[1,0]
	v_pk_mul_f32 v[66:67], v[66:67], v[236:237] op_sel_hi:[1,0]
	v_pk_fma_f32 v[146:147], v[176:177], v[68:69], v[180:181]
	v_pk_fma_f32 v[148:149], v[178:179], v[70:71], v[182:183]
	v_fmac_f32_dpp v146, v68, v172 row_shr:1 row_mask:0xf bank_mask:0xf bound_ctrl:1
	v_fmac_f32_dpp v147, v69, v173 row_shr:1 row_mask:0xf bank_mask:0xf bound_ctrl:1
	v_fmac_f32_dpp v148, v70, v174 row_shr:1 row_mask:0xf bank_mask:0xf bound_ctrl:1
	v_fmac_f32_dpp v149, v71, v175 row_shr:1 row_mask:0xf bank_mask:0xf bound_ctrl:1
	v_fmac_f32_dpp v146, v76, v172 row_shl:15 row_mask:0xf bank_mask:0xf
	v_fmac_f32_dpp v147, v77, v173 row_shl:15 row_mask:0xf bank_mask:0xf
	v_fmac_f32_dpp v148, v78, v174 row_shl:15 row_mask:0xf bank_mask:0xf
	v_fmac_f32_dpp v149, v79, v175 row_shl:15 row_mask:0xf bank_mask:0xf
	v_fmac_f32_dpp v146, v68, v168 row_shr:2 row_mask:0xf bank_mask:0xf bound_ctrl:1
	v_fmac_f32_dpp v147, v69, v169 row_shr:2 row_mask:0xf bank_mask:0xf bound_ctrl:1
	v_fmac_f32_dpp v148, v70, v170 row_shr:2 row_mask:0xf bank_mask:0xf bound_ctrl:1
	v_fmac_f32_dpp v149, v71, v171 row_shr:2 row_mask:0xf bank_mask:0xf bound_ctrl:1
	v_fmac_f32_dpp v146, v76, v168 row_shl:14 row_mask:0xf bank_mask:0xf
	v_fmac_f32_dpp v147, v77, v169 row_shl:14 row_mask:0xf bank_mask:0xf
	v_fmac_f32_dpp v148, v78, v170 row_shl:14 row_mask:0xf bank_mask:0xf
	v_fmac_f32_dpp v149, v79, v171 row_shl:14 row_mask:0xf bank_mask:0xf
	v_exp_f32_e32 v242, v146
	v_exp_f32_e32 v243, v147
	v_exp_f32_e32 v244, v148
	v_exp_f32_e32 v245, v149
	v_pk_mul_f32 v[146:147], v[146:147], v[64:65]
	v_pk_mul_f32 v[148:149], v[148:149], v[66:67]
	v_pk_add_f32 v[242:243], v[242:243], 1.0 op_sel_hi:[1,0]
	v_pk_add_f32 v[244:245], v[244:245], 1.0 op_sel_hi:[1,0]
	v_rcp_f32_e32 v242, v242
	v_rcp_f32_e32 v243, v243
	v_rcp_f32_e32 v244, v244
	v_rcp_f32_e32 v245, v245
	v_cvt_pk_bf16_f32 v66, v68, v69
	v_cvt_pk_bf16_f32 v67, v70, v71
	v_pk_mul_f32 v[146:147], v[146:147], v[242:243]
	v_pk_mul_f32 v[148:149], v[148:149], v[244:245]
	s_mov_b32 s100, 0xffffd400
	s_mov_b32 s101, -1
	s_and_saveexec_b64 s[6:7], s[42:43]
	v_lshl_add_u64 v[150:151], v[246:247], 0, s[100:101]
	global_store_dwordx2 v[150:151], v[66:67], off
	s_or_b64 exec, exec, s[6:7]
	v_cvt_pk_bf16_f32 v64, v146, v147
	v_cvt_pk_bf16_f32 v65, v148, v149
	s_and_saveexec_b64 s[6:7], s[40:41]
	v_pk_mul_f32 v[242:243], v[56:57], v[206:207] op_sel_hi:[1,0]
	v_pk_mul_f32 v[244:245], v[58:59], v[206:207] op_sel_hi:[1,0]
	s_mov_b32 s100, 0x5808
	s_mov_b32 s101, 0
	v_cvt_pk_bf16_f32 v242, v242, v243
	v_cvt_pk_bf16_f32 v243, v244, v245
	v_lshl_add_u64 v[150:151], v[246:247], 0, s[100:101]
	global_store_dwordx2 v[150:151], v[242:243], off
	s_or_b64 exec, exec, s[6:7]
	v_pk_mul_f32 v[60:61], v[60:61], v[206:207] op_sel_hi:[1,0]
	v_pk_mul_f32 v[62:63], v[62:63], v[206:207] op_sel_hi:[1,0]
	v_pk_mul_f32 v[56:57], v[56:57], v[208:209] op_sel_hi:[1,0]
	v_pk_mul_f32 v[58:59], v[58:59], v[208:209] op_sel_hi:[1,0]
	v_pk_fma_f32 v[146:147], v[200:201], v[60:61], v[238:239]
	v_pk_fma_f32 v[148:149], v[202:203], v[62:63], v[240:241]
	v_fmac_f32_dpp v146, v60, v196 row_shr:1 row_mask:0xf bank_mask:0xf bound_ctrl:1
	v_fmac_f32_dpp v147, v61, v197 row_shr:1 row_mask:0xf bank_mask:0xf bound_ctrl:1
	v_fmac_f32_dpp v148, v62, v198 row_shr:1 row_mask:0xf bank_mask:0xf bound_ctrl:1
	v_fmac_f32_dpp v149, v63, v199 row_shr:1 row_mask:0xf bank_mask:0xf bound_ctrl:1
	v_fmac_f32_dpp v146, v60, v192 row_shr:2 row_mask:0xf bank_mask:0xf bound_ctrl:1
	v_fmac_f32_dpp v147, v61, v193 row_shr:2 row_mask:0xf bank_mask:0xf bound_ctrl:1
	v_fmac_f32_dpp v148, v62, v194 row_shr:2 row_mask:0xf bank_mask:0xf bound_ctrl:1
	v_fmac_f32_dpp v149, v63, v195 row_shr:2 row_mask:0xf bank_mask:0xf bound_ctrl:1
	v_exp_f32_e32 v242, v146
	v_exp_f32_e32 v243, v147
	v_exp_f32_e32 v244, v148
	v_exp_f32_e32 v245, v149
	v_pk_mul_f32 v[146:147], v[146:147], v[56:57]
	v_pk_mul_f32 v[148:149], v[148:149], v[58:59]
	v_pk_add_f32 v[242:243], v[242:243], 1.0 op_sel_hi:[1,0]
	v_pk_add_f32 v[244:245], v[244:245], 1.0 op_sel_hi:[1,0]
	v_rcp_f32_e32 v242, v242
	v_rcp_f32_e32 v243, v243
	v_rcp_f32_e32 v244, v244
	v_rcp_f32_e32 v245, v245
	v_cvt_pk_bf16_f32 v56, v60, v61
	v_cvt_pk_bf16_f32 v57, v62, v63
	v_pk_mul_f32 v[146:147], v[146:147], v[242:243]
	v_pk_mul_f32 v[148:149], v[148:149], v[244:245]
	s_mov_b32 s100, 0x2c08
	s_mov_b32 s101, 0
	s_and_saveexec_b64 s[6:7], s[40:41]
	v_lshl_add_u64 v[150:151], v[246:247], 0, s[100:101]
	global_store_dwordx2 v[150:151], v[56:57], off
	s_or_b64 exec, exec, s[6:7]
	v_cvt_pk_bf16_f32 v126, v146, v147
	v_cvt_pk_bf16_f32 v127, v148, v149
	s_mov_b32 s5, 0x0
	s_and_saveexec_b64 s[6:7], s[38:39]
	buffer_store_dwordx4 v[124:127], v185, s[52:55], s5 offen sc1 nt
	s_or_b64 exec, exec, s[6:7]
	v_pk_mul_f32 v[52:53], v[52:53], v[210:211] op_sel_hi:[1,0]
	v_pk_mul_f32 v[54:55], v[54:55], v[210:211] op_sel_hi:[1,0]
	v_pk_mul_f32 v[48:49], v[48:49], v[212:213] op_sel_hi:[1,0]
	v_pk_mul_f32 v[50:51], v[50:51], v[212:213] op_sel_hi:[1,0]
	v_pk_fma_f32 v[146:147], v[200:201], v[52:53], v[238:239]
	v_pk_fma_f32 v[148:149], v[202:203], v[54:55], v[240:241]
	v_fmac_f32_dpp v146, v52, v196 row_shr:1 row_mask:0xf bank_mask:0xf bound_ctrl:1
	v_fmac_f32_dpp v147, v53, v197 row_shr:1 row_mask:0xf bank_mask:0xf bound_ctrl:1
	v_fmac_f32_dpp v148, v54, v198 row_shr:1 row_mask:0xf bank_mask:0xf bound_ctrl:1
	v_fmac_f32_dpp v149, v55, v199 row_shr:1 row_mask:0xf bank_mask:0xf bound_ctrl:1
	v_fmac_f32_dpp v146, v60, v196 row_shl:15 row_mask:0xf bank_mask:0xf
	v_fmac_f32_dpp v147, v61, v197 row_shl:15 row_mask:0xf bank_mask:0xf
	v_fmac_f32_dpp v148, v62, v198 row_shl:15 row_mask:0xf bank_mask:0xf
	v_fmac_f32_dpp v149, v63, v199 row_shl:15 row_mask:0xf bank_mask:0xf
	v_fmac_f32_dpp v146, v52, v192 row_shr:2 row_mask:0xf bank_mask:0xf bound_ctrl:1
	v_fmac_f32_dpp v147, v53, v193 row_shr:2 row_mask:0xf bank_mask:0xf bound_ctrl:1
	v_fmac_f32_dpp v148, v54, v194 row_shr:2 row_mask:0xf bank_mask:0xf bound_ctrl:1
	v_fmac_f32_dpp v149, v55, v195 row_shr:2 row_mask:0xf bank_mask:0xf bound_ctrl:1
	v_fmac_f32_dpp v146, v60, v192 row_shl:14 row_mask:0xf bank_mask:0xf
	v_fmac_f32_dpp v147, v61, v193 row_shl:14 row_mask:0xf bank_mask:0xf
	v_fmac_f32_dpp v148, v62, v194 row_shl:14 row_mask:0xf bank_mask:0xf
	v_fmac_f32_dpp v149, v63, v195 row_shl:14 row_mask:0xf bank_mask:0xf
	v_exp_f32_e32 v242, v146
	v_exp_f32_e32 v243, v147
	v_exp_f32_e32 v244, v148
	v_exp_f32_e32 v245, v149
	v_pk_mul_f32 v[146:147], v[146:147], v[48:49]
	v_pk_mul_f32 v[148:149], v[148:149], v[50:51]
	v_pk_add_f32 v[242:243], v[242:243], 1.0 op_sel_hi:[1,0]
	v_pk_add_f32 v[244:245], v[244:245], 1.0 op_sel_hi:[1,0]
	v_rcp_f32_e32 v242, v242
	v_rcp_f32_e32 v243, v243
	v_rcp_f32_e32 v244, v244
	v_rcp_f32_e32 v245, v245
	s_nop 0
	v_pk_mul_f32 v[146:147], v[146:147], v[242:243]
	v_pk_mul_f32 v[148:149], v[148:149], v[244:245]
	v_cvt_pk_bf16_f32 v118, v146, v147
	v_cvt_pk_bf16_f32 v119, v148, v149
	s_mov_b32 s5, 0x16000
	buffer_store_dwordx4 v[116:119], v185, s[52:55], s5 offen sc1 nt
	v_pk_mul_f32 v[44:45], v[44:45], v[214:215] op_sel_hi:[1,0]
	v_pk_mul_f32 v[46:47], v[46:47], v[214:215] op_sel_hi:[1,0]
	v_pk_mul_f32 v[40:41], v[40:41], v[216:217] op_sel_hi:[1,0]
	v_pk_mul_f32 v[42:43], v[42:43], v[216:217] op_sel_hi:[1,0]
	v_pk_fma_f32 v[146:147], v[200:201], v[44:45], v[238:239]
	v_pk_fma_f32 v[148:149], v[202:203], v[46:47], v[240:241]
	v_fmac_f32_dpp v146, v44, v196 row_shr:1 row_mask:0xf bank_mask:0xf bound_ctrl:1
	v_fmac_f32_dpp v147, v45, v197 row_shr:1 row_mask:0xf bank_mask:0xf bound_ctrl:1
	v_fmac_f32_dpp v148, v46, v198 row_shr:1 row_mask:0xf bank_mask:0xf bound_ctrl:1
	v_fmac_f32_dpp v149, v47, v199 row_shr:1 row_mask:0xf bank_mask:0xf bound_ctrl:1
	v_fmac_f32_dpp v146, v52, v196 row_shl:15 row_mask:0xf bank_mask:0xf
	v_fmac_f32_dpp v147, v53, v197 row_shl:15 row_mask:0xf bank_mask:0xf
	v_fmac_f32_dpp v148, v54, v198 row_shl:15 row_mask:0xf bank_mask:0xf
	v_fmac_f32_dpp v149, v55, v199 row_shl:15 row_mask:0xf bank_mask:0xf
	v_fmac_f32_dpp v146, v44, v192 row_shr:2 row_mask:0xf bank_mask:0xf bound_ctrl:1
	v_fmac_f32_dpp v147, v45, v193 row_shr:2 row_mask:0xf bank_mask:0xf bound_ctrl:1
	v_fmac_f32_dpp v148, v46, v194 row_shr:2 row_mask:0xf bank_mask:0xf bound_ctrl:1
	v_fmac_f32_dpp v149, v47, v195 row_shr:2 row_mask:0xf bank_mask:0xf bound_ctrl:1
	v_fmac_f32_dpp v146, v52, v192 row_shl:14 row_mask:0xf bank_mask:0xf
	v_fmac_f32_dpp v147, v53, v193 row_shl:14 row_mask:0xf bank_mask:0xf
	v_fmac_f32_dpp v148, v54, v194 row_shl:14 row_mask:0xf bank_mask:0xf
	v_fmac_f32_dpp v149, v55, v195 row_shl:14 row_mask:0xf bank_mask:0xf
	v_exp_f32_e32 v242, v146
	v_exp_f32_e32 v243, v147
	v_exp_f32_e32 v244, v148
	v_exp_f32_e32 v245, v149
	v_pk_mul_f32 v[146:147], v[146:147], v[40:41]
	v_pk_mul_f32 v[148:149], v[148:149], v[42:43]
	v_pk_add_f32 v[242:243], v[242:243], 1.0 op_sel_hi:[1,0]
	v_pk_add_f32 v[244:245], v[244:245], 1.0 op_sel_hi:[1,0]
	v_rcp_f32_e32 v242, v242
	v_rcp_f32_e32 v243, v243
	v_rcp_f32_e32 v244, v244
	v_rcp_f32_e32 v245, v245
	s_nop 0
	v_pk_mul_f32 v[146:147], v[146:147], v[242:243]
	v_pk_mul_f32 v[148:149], v[148:149], v[244:245]
	v_cvt_pk_bf16_f32 v100, v146, v147
	v_cvt_pk_bf16_f32 v101, v148, v149
	s_mov_b32 s5, 0x2c000
	buffer_store_dwordx4 v[98:101], v185, s[52:55], s5 offen sc1 nt
	v_pk_mul_f32 v[36:37], v[36:37], v[218:219] op_sel_hi:[1,0]
	v_pk_mul_f32 v[38:39], v[38:39], v[218:219] op_sel_hi:[1,0]
	v_pk_mul_f32 v[32:33], v[32:33], v[220:221] op_sel_hi:[1,0]
	v_pk_mul_f32 v[34:35], v[34:35], v[220:221] op_sel_hi:[1,0]
	v_pk_fma_f32 v[146:147], v[200:201], v[36:37], v[238:239]
	v_pk_fma_f32 v[148:149], v[202:203], v[38:39], v[240:241]
	v_fmac_f32_dpp v146, v36, v196 row_shr:1 row_mask:0xf bank_mask:0xf bound_ctrl:1
	v_fmac_f32_dpp v147, v37, v197 row_shr:1 row_mask:0xf bank_mask:0xf bound_ctrl:1
	v_fmac_f32_dpp v148, v38, v198 row_shr:1 row_mask:0xf bank_mask:0xf bound_ctrl:1
	v_fmac_f32_dpp v149, v39, v199 row_shr:1 row_mask:0xf bank_mask:0xf bound_ctrl:1
	v_fmac_f32_dpp v146, v44, v196 row_shl:15 row_mask:0xf bank_mask:0xf
	v_fmac_f32_dpp v147, v45, v197 row_shl:15 row_mask:0xf bank_mask:0xf
	v_fmac_f32_dpp v148, v46, v198 row_shl:15 row_mask:0xf bank_mask:0xf
	v_fmac_f32_dpp v149, v47, v199 row_shl:15 row_mask:0xf bank_mask:0xf
	v_fmac_f32_dpp v146, v36, v192 row_shr:2 row_mask:0xf bank_mask:0xf bound_ctrl:1
	v_fmac_f32_dpp v147, v37, v193 row_shr:2 row_mask:0xf bank_mask:0xf bound_ctrl:1
	v_fmac_f32_dpp v148, v38, v194 row_shr:2 row_mask:0xf bank_mask:0xf bound_ctrl:1
	v_fmac_f32_dpp v149, v39, v195 row_shr:2 row_mask:0xf bank_mask:0xf bound_ctrl:1
	v_fmac_f32_dpp v146, v44, v192 row_shl:14 row_mask:0xf bank_mask:0xf
	v_fmac_f32_dpp v147, v45, v193 row_shl:14 row_mask:0xf bank_mask:0xf
	v_fmac_f32_dpp v148, v46, v194 row_shl:14 row_mask:0xf bank_mask:0xf
	v_fmac_f32_dpp v149, v47, v195 row_shl:14 row_mask:0xf bank_mask:0xf
	v_exp_f32_e32 v242, v146
	v_exp_f32_e32 v243, v147
	v_exp_f32_e32 v244, v148
	v_exp_f32_e32 v245, v149
	v_pk_mul_f32 v[146:147], v[146:147], v[32:33]
	v_pk_mul_f32 v[148:149], v[148:149], v[34:35]
	v_pk_add_f32 v[242:243], v[242:243], 1.0 op_sel_hi:[1,0]
	v_pk_add_f32 v[244:245], v[244:245], 1.0 op_sel_hi:[1,0]
	v_rcp_f32_e32 v242, v242
	v_rcp_f32_e32 v243, v243
	v_rcp_f32_e32 v244, v244
	v_rcp_f32_e32 v245, v245
	v_cvt_pk_bf16_f32 v32, v36, v37
	v_cvt_pk_bf16_f32 v33, v38, v39
	v_pk_mul_f32 v[146:147], v[146:147], v[242:243]
	v_pk_mul_f32 v[148:149], v[148:149], v[244:245]
	s_mov_b32 s100, 0xfffecc08
	s_mov_b32 s101, -1
	s_and_saveexec_b64 s[6:7], s[42:43]
	v_lshl_add_u64 v[150:151], v[246:247], 0, s[100:101]
	global_store_dwordx2 v[150:151], v[32:33], off
	s_or_b64 exec, exec, s[6:7]
	v_cvt_pk_bf16_f32 v106, v146, v147
	v_cvt_pk_bf16_f32 v107, v148, v149
	s_mov_b32 s5, 0x42000
	buffer_store_dwordx4 v[104:107], v185, s[52:55], s5 offen sc1 nt
	s_and_saveexec_b64 s[6:7], s[40:41]
	v_pk_mul_f32 v[242:243], v[24:25], v[222:223] op_sel_hi:[1,0]
	v_pk_mul_f32 v[244:245], v[26:27], v[222:223] op_sel_hi:[1,0]
	s_mov_b32 s100, 0x16008
	s_mov_b32 s101, 0
	v_cvt_pk_bf16_f32 v242, v242, v243
	v_cvt_pk_bf16_f32 v243, v244, v245
	v_lshl_add_u64 v[150:151], v[246:247], 0, s[100:101]
	global_store_dwordx2 v[150:151], v[242:243], off
	s_or_b64 exec, exec, s[6:7]
	v_pk_mul_f32 v[28:29], v[28:29], v[222:223] op_sel_hi:[1,0]
	v_pk_mul_f32 v[30:31], v[30:31], v[222:223] op_sel_hi:[1,0]
	v_pk_mul_f32 v[24:25], v[24:25], v[224:225] op_sel_hi:[1,0]
	v_pk_mul_f32 v[26:27], v[26:27], v[224:225] op_sel_hi:[1,0]
	v_pk_fma_f32 v[146:147], v[200:201], v[28:29], v[238:239]
	v_pk_fma_f32 v[148:149], v[202:203], v[30:31], v[240:241]
	v_fmac_f32_dpp v146, v28, v196 row_shr:1 row_mask:0xf bank_mask:0xf bound_ctrl:1
	v_fmac_f32_dpp v147, v29, v197 row_shr:1 row_mask:0xf bank_mask:0xf bound_ctrl:1
	v_fmac_f32_dpp v148, v30, v198 row_shr:1 row_mask:0xf bank_mask:0xf bound_ctrl:1
	v_fmac_f32_dpp v149, v31, v199 row_shr:1 row_mask:0xf bank_mask:0xf bound_ctrl:1
	v_fmac_f32_dpp v146, v28, v192 row_shr:2 row_mask:0xf bank_mask:0xf bound_ctrl:1
	v_fmac_f32_dpp v147, v29, v193 row_shr:2 row_mask:0xf bank_mask:0xf bound_ctrl:1
	v_fmac_f32_dpp v148, v30, v194 row_shr:2 row_mask:0xf bank_mask:0xf bound_ctrl:1
	v_fmac_f32_dpp v149, v31, v195 row_shr:2 row_mask:0xf bank_mask:0xf bound_ctrl:1
	v_exp_f32_e32 v242, v146
	v_exp_f32_e32 v243, v147
	v_exp_f32_e32 v244, v148
	v_exp_f32_e32 v245, v149
	v_pk_mul_f32 v[146:147], v[146:147], v[24:25]
	v_pk_mul_f32 v[148:149], v[148:149], v[26:27]
	v_pk_add_f32 v[242:243], v[242:243], 1.0 op_sel_hi:[1,0]
	v_pk_add_f32 v[244:245], v[244:245], 1.0 op_sel_hi:[1,0]
	v_rcp_f32_e32 v242, v242
	v_rcp_f32_e32 v243, v243
	v_rcp_f32_e32 v244, v244
	v_rcp_f32_e32 v245, v245
	v_cvt_pk_bf16_f32 v24, v28, v29
	v_cvt_pk_bf16_f32 v25, v30, v31
	v_pk_mul_f32 v[146:147], v[146:147], v[242:243]
	v_pk_mul_f32 v[148:149], v[148:149], v[244:245]
	s_mov_b32 s100, 0x13408
	s_mov_b32 s101, 0
	s_and_saveexec_b64 s[6:7], s[40:41]
	v_lshl_add_u64 v[150:151], v[246:247], 0, s[100:101]
	global_store_dwordx2 v[150:151], v[24:25], off
	s_or_b64 exec, exec, s[6:7]
	v_cvt_pk_bf16_f32 v90, v146, v147
	v_cvt_pk_bf16_f32 v91, v148, v149
	s_mov_b32 s5, 0xb0000
	s_and_saveexec_b64 s[6:7], s[38:39]
	buffer_store_dwordx4 v[88:91], v185, s[52:55], s5 offen sc1 nt
	s_or_b64 exec, exec, s[6:7]
	v_pk_mul_f32 v[20:21], v[20:21], v[226:227] op_sel_hi:[1,0]
	v_pk_mul_f32 v[22:23], v[22:23], v[226:227] op_sel_hi:[1,0]
	v_pk_mul_f32 v[16:17], v[16:17], v[228:229] op_sel_hi:[1,0]
	v_pk_mul_f32 v[18:19], v[18:19], v[228:229] op_sel_hi:[1,0]
	v_pk_fma_f32 v[146:147], v[200:201], v[20:21], v[238:239]
	v_pk_fma_f32 v[148:149], v[202:203], v[22:23], v[240:241]
	v_fmac_f32_dpp v146, v20, v196 row_shr:1 row_mask:0xf bank_mask:0xf bound_ctrl:1
	v_fmac_f32_dpp v147, v21, v197 row_shr:1 row_mask:0xf bank_mask:0xf bound_ctrl:1
	v_fmac_f32_dpp v148, v22, v198 row_shr:1 row_mask:0xf bank_mask:0xf bound_ctrl:1
	v_fmac_f32_dpp v149, v23, v199 row_shr:1 row_mask:0xf bank_mask:0xf bound_ctrl:1
	v_fmac_f32_dpp v146, v28, v196 row_shl:15 row_mask:0xf bank_mask:0xf
	v_fmac_f32_dpp v147, v29, v197 row_shl:15 row_mask:0xf bank_mask:0xf
	v_fmac_f32_dpp v148, v30, v198 row_shl:15 row_mask:0xf bank_mask:0xf
	v_fmac_f32_dpp v149, v31, v199 row_shl:15 row_mask:0xf bank_mask:0xf
	v_fmac_f32_dpp v146, v20, v192 row_shr:2 row_mask:0xf bank_mask:0xf bound_ctrl:1
	v_fmac_f32_dpp v147, v21, v193 row_shr:2 row_mask:0xf bank_mask:0xf bound_ctrl:1
	v_fmac_f32_dpp v148, v22, v194 row_shr:2 row_mask:0xf bank_mask:0xf bound_ctrl:1
	v_fmac_f32_dpp v149, v23, v195 row_shr:2 row_mask:0xf bank_mask:0xf bound_ctrl:1
	v_fmac_f32_dpp v146, v28, v192 row_shl:14 row_mask:0xf bank_mask:0xf
	v_fmac_f32_dpp v147, v29, v193 row_shl:14 row_mask:0xf bank_mask:0xf
	v_fmac_f32_dpp v148, v30, v194 row_shl:14 row_mask:0xf bank_mask:0xf
	v_fmac_f32_dpp v149, v31, v195 row_shl:14 row_mask:0xf bank_mask:0xf
	v_exp_f32_e32 v242, v146
	v_exp_f32_e32 v243, v147
	v_exp_f32_e32 v244, v148
	v_exp_f32_e32 v245, v149
	v_pk_mul_f32 v[146:147], v[146:147], v[16:17]
	v_pk_mul_f32 v[148:149], v[148:149], v[18:19]
	v_pk_add_f32 v[242:243], v[242:243], 1.0 op_sel_hi:[1,0]
	v_pk_add_f32 v[244:245], v[244:245], 1.0 op_sel_hi:[1,0]
	v_rcp_f32_e32 v242, v242
	v_rcp_f32_e32 v243, v243
	v_rcp_f32_e32 v244, v244
	v_rcp_f32_e32 v245, v245
	s_nop 0
	v_pk_mul_f32 v[146:147], v[146:147], v[242:243]
	v_pk_mul_f32 v[148:149], v[148:149], v[244:245]
	v_cvt_pk_bf16_f32 v82, v146, v147
	v_cvt_pk_bf16_f32 v83, v148, v149
	s_mov_b32 s5, 0xc6000
	buffer_store_dwordx4 v[80:83], v185, s[52:55], s5 offen sc1 nt
	v_pk_mul_f32 v[12:13], v[12:13], v[230:231] op_sel_hi:[1,0]
	v_pk_mul_f32 v[14:15], v[14:15], v[230:231] op_sel_hi:[1,0]
	v_pk_mul_f32 v[8:9], v[8:9], v[232:233] op_sel_hi:[1,0]
	v_pk_mul_f32 v[10:11], v[10:11], v[232:233] op_sel_hi:[1,0]
	v_pk_fma_f32 v[146:147], v[200:201], v[12:13], v[238:239]
	v_pk_fma_f32 v[148:149], v[202:203], v[14:15], v[240:241]
	v_fmac_f32_dpp v146, v12, v196 row_shr:1 row_mask:0xf bank_mask:0xf bound_ctrl:1
	v_fmac_f32_dpp v147, v13, v197 row_shr:1 row_mask:0xf bank_mask:0xf bound_ctrl:1
	v_fmac_f32_dpp v148, v14, v198 row_shr:1 row_mask:0xf bank_mask:0xf bound_ctrl:1
	v_fmac_f32_dpp v149, v15, v199 row_shr:1 row_mask:0xf bank_mask:0xf bound_ctrl:1
	v_fmac_f32_dpp v146, v20, v196 row_shl:15 row_mask:0xf bank_mask:0xf
	v_fmac_f32_dpp v147, v21, v197 row_shl:15 row_mask:0xf bank_mask:0xf
	v_fmac_f32_dpp v148, v22, v198 row_shl:15 row_mask:0xf bank_mask:0xf
	v_fmac_f32_dpp v149, v23, v199 row_shl:15 row_mask:0xf bank_mask:0xf
	v_fmac_f32_dpp v146, v12, v192 row_shr:2 row_mask:0xf bank_mask:0xf bound_ctrl:1
	v_fmac_f32_dpp v147, v13, v193 row_shr:2 row_mask:0xf bank_mask:0xf bound_ctrl:1
	v_fmac_f32_dpp v148, v14, v194 row_shr:2 row_mask:0xf bank_mask:0xf bound_ctrl:1
	v_fmac_f32_dpp v149, v15, v195 row_shr:2 row_mask:0xf bank_mask:0xf bound_ctrl:1
	v_fmac_f32_dpp v146, v20, v192 row_shl:14 row_mask:0xf bank_mask:0xf
	v_fmac_f32_dpp v147, v21, v193 row_shl:14 row_mask:0xf bank_mask:0xf
	v_fmac_f32_dpp v148, v22, v194 row_shl:14 row_mask:0xf bank_mask:0xf
	v_fmac_f32_dpp v149, v23, v195 row_shl:14 row_mask:0xf bank_mask:0xf
	v_exp_f32_e32 v242, v146
	v_exp_f32_e32 v243, v147
	v_exp_f32_e32 v244, v148
	v_exp_f32_e32 v245, v149
	v_pk_mul_f32 v[146:147], v[146:147], v[8:9]
	v_pk_mul_f32 v[148:149], v[148:149], v[10:11]
	v_pk_add_f32 v[242:243], v[242:243], 1.0 op_sel_hi:[1,0]
	v_pk_add_f32 v[244:245], v[244:245], 1.0 op_sel_hi:[1,0]
	v_rcp_f32_e32 v242, v242
	v_rcp_f32_e32 v243, v243
	v_rcp_f32_e32 v244, v244
	v_rcp_f32_e32 v245, v245
	s_nop 0
	v_pk_mul_f32 v[146:147], v[146:147], v[242:243]
	v_pk_mul_f32 v[148:149], v[148:149], v[244:245]
	v_cvt_pk_bf16_f32 v74, v146, v147
	v_cvt_pk_bf16_f32 v75, v148, v149
	s_mov_b32 s5, 0xdc000
	buffer_store_dwordx4 v[72:75], v185, s[52:55], s5 offen sc1 nt
	v_pk_mul_f32 v[4:5], v[4:5], v[234:235] op_sel_hi:[1,0]
	v_pk_mul_f32 v[6:7], v[6:7], v[234:235] op_sel_hi:[1,0]
	v_pk_mul_f32 v[0:1], v[0:1], v[236:237] op_sel_hi:[1,0]
	v_pk_mul_f32 v[2:3], v[2:3], v[236:237] op_sel_hi:[1,0]
	v_pk_fma_f32 v[146:147], v[200:201], v[4:5], v[238:239]
	v_pk_fma_f32 v[148:149], v[202:203], v[6:7], v[240:241]
	v_fmac_f32_dpp v146, v4, v196 row_shr:1 row_mask:0xf bank_mask:0xf bound_ctrl:1
	v_fmac_f32_dpp v147, v5, v197 row_shr:1 row_mask:0xf bank_mask:0xf bound_ctrl:1
	v_fmac_f32_dpp v148, v6, v198 row_shr:1 row_mask:0xf bank_mask:0xf bound_ctrl:1
	v_fmac_f32_dpp v149, v7, v199 row_shr:1 row_mask:0xf bank_mask:0xf bound_ctrl:1
	v_fmac_f32_dpp v146, v12, v196 row_shl:15 row_mask:0xf bank_mask:0xf
	v_fmac_f32_dpp v147, v13, v197 row_shl:15 row_mask:0xf bank_mask:0xf
	v_fmac_f32_dpp v148, v14, v198 row_shl:15 row_mask:0xf bank_mask:0xf
	v_fmac_f32_dpp v149, v15, v199 row_shl:15 row_mask:0xf bank_mask:0xf
	v_fmac_f32_dpp v146, v4, v192 row_shr:2 row_mask:0xf bank_mask:0xf bound_ctrl:1
	v_fmac_f32_dpp v147, v5, v193 row_shr:2 row_mask:0xf bank_mask:0xf bound_ctrl:1
	v_fmac_f32_dpp v148, v6, v194 row_shr:2 row_mask:0xf bank_mask:0xf bound_ctrl:1
	v_fmac_f32_dpp v149, v7, v195 row_shr:2 row_mask:0xf bank_mask:0xf bound_ctrl:1
	v_fmac_f32_dpp v146, v12, v192 row_shl:14 row_mask:0xf bank_mask:0xf
	v_fmac_f32_dpp v147, v13, v193 row_shl:14 row_mask:0xf bank_mask:0xf
	v_fmac_f32_dpp v148, v14, v194 row_shl:14 row_mask:0xf bank_mask:0xf
	v_fmac_f32_dpp v149, v15, v195 row_shl:14 row_mask:0xf bank_mask:0xf
	v_exp_f32_e32 v242, v146
	v_exp_f32_e32 v243, v147
	v_exp_f32_e32 v244, v148
	v_exp_f32_e32 v245, v149
	v_pk_mul_f32 v[146:147], v[146:147], v[0:1]
	v_pk_mul_f32 v[148:149], v[148:149], v[2:3]
	v_pk_add_f32 v[242:243], v[242:243], 1.0 op_sel_hi:[1,0]
	v_pk_add_f32 v[244:245], v[244:245], 1.0 op_sel_hi:[1,0]
	v_rcp_f32_e32 v242, v242
	v_rcp_f32_e32 v243, v243
	v_rcp_f32_e32 v244, v244
	v_rcp_f32_e32 v245, v245
	v_cvt_pk_bf16_f32 v0, v4, v5
	v_cvt_pk_bf16_f32 v1, v6, v7
	v_pk_mul_f32 v[146:147], v[146:147], v[242:243]
	v_pk_mul_f32 v[148:149], v[148:149], v[244:245]
	s_mov_b32 s100, 0xffffd408
	s_mov_b32 s101, -1
	s_and_saveexec_b64 s[6:7], s[42:43]
	v_lshl_add_u64 v[150:151], v[246:247], 0, s[100:101]
	global_store_dwordx2 v[150:151], v[0:1], off
	s_or_b64 exec, exec, s[6:7]
	v_cvt_pk_bf16_f32 v66, v146, v147
	v_cvt_pk_bf16_f32 v67, v148, v149
	s_mov_b32 s5, 0xf2000
	buffer_store_dwordx4 v[64:67], v185, s[52:55], s5 offen sc1 nt
	s_andn2_b64 vcc, exec, s[44:45]
	s_mov_b64 s[6:7], -1
	s_cbranch_vccnz .LBB0_716
	s_andn2_b64 vcc, exec, s[28:29]
	s_cbranch_vccnz .LBB0_715
	s_barrier
	s_branch .LBB0_715
